# prompt-attention tile (near and far paths): 8 K-fragment ds_read_b128 + 16 bias-table ds_read_b32 issued up front into separate registers, QK^T MFMAs behind counted lgkmcnt, instead of hipcc read/wait
# speedup vs baseline: 1.0010x; 1.0010x over previous
.LBB0_502:
	v_add_u32_e32 v8, 0x22050, v242
	ds_read_b32 v50, v8 offset:432
	ds_read_b32 v51, v8 offset:416
	ds_read_b32 v52, v8 offset:400
	ds_read_b32 v53, v8 offset:384
	ds_read_b32 v54, v8 offset:304
	ds_read_b32 v55, v8 offset:288
	ds_read_b32 v56, v8 offset:272
	ds_read_b32 v57, v8 offset:256
	ds_read_b32 v58, v8 offset:176
	ds_read_b32 v59, v8 offset:160
	ds_read_b32 v60, v8 offset:144
	ds_read_b32 v61, v8 offset:128
	ds_read_b32 v62, v8 offset:48
	ds_read_b32 v63, v8 offset:32
	ds_read_b32 v64, v8 offset:16
	ds_read_b32 v65, v8
	ds_read_b128 v[18:21], v13
	ds_read_b128 v[22:25], v14
	ds_read_b128 v[26:29], v15
	ds_read_b128 v[30:33], v16
	ds_read_b128 v[34:37], v17
	ds_read_b128 v[38:41], v238
	ds_read_b128 v[42:45], v240
	ds_read_b128 v[46:49], v239
	s_waitcnt lgkmcnt(7)
	v_mfma_f32_32x32x16_bf16 v[146:161], v[18:21], v[162:165], 0
	s_waitcnt lgkmcnt(6)
	v_mfma_f32_32x32x16_bf16 v[146:161], v[22:25], v[166:169], v[146:161]
	s_waitcnt lgkmcnt(5)
	v_mfma_f32_32x32x16_bf16 v[146:161], v[26:29], v[170:173], v[146:161]
	s_waitcnt lgkmcnt(4)
	v_mfma_f32_32x32x16_bf16 v[146:161], v[30:33], v[174:177], v[146:161]
	s_waitcnt lgkmcnt(3)
	v_mfma_f32_32x32x16_bf16 v[146:161], v[34:37], v[178:181], v[146:161]
	s_waitcnt lgkmcnt(2)
	v_mfma_f32_32x32x16_bf16 v[146:161], v[38:41], v[182:185], v[146:161]
	s_waitcnt lgkmcnt(1)
	v_mfma_f32_32x32x16_bf16 v[146:161], v[42:45], v[186:189], v[146:161]
	s_waitcnt lgkmcnt(0)
	v_mfma_f32_32x32x16_bf16 v[146:161], v[46:49], v[190:193], v[146:161]
	s_nop 7
	s_nop 4
	v_add_f32_e32 v4, v146, v50
	v_add_f32_e32 v5, v147, v51
	v_add_f32_e32 v6, v148, v52
	v_add_f32_e32 v7, v149, v53
	v_add_f32_e32 v9, v150, v54
	v_add_f32_e32 v10, v151, v55
	v_add_f32_e32 v11, v152, v56
	v_add_f32_e32 v147, v153, v57
	v_add_f32_e32 v148, v154, v58
	v_add_f32_e32 v149, v155, v59
	v_add_f32_e32 v150, v156, v60
	v_add_f32_e32 v151, v157, v61
	v_add_f32_e32 v152, v158, v62
	v_add_f32_e32 v153, v159, v63
	v_add_f32_e32 v154, v160, v64
	v_add_f32_e32 v8, v161, v65
	v_max_f32_e32 v146, v4, v5
	v_max3_f32 v146, v146, v6, v7
	v_max3_f32 v146, v146, v9, v10
	v_max3_f32 v146, v146, v11, v147
	v_max3_f32 v146, v146, v148, v149
	v_max3_f32 v146, v146, v150, v151
	v_max3_f32 v146, v146, v152, v153
	v_max3_f32 v146, v146, v154, v8
	ds_bpermute_b32 v155, v241, v146
	s_waitcnt lgkmcnt(0)
	v_max_f32_e32 v155, v155, v155
	v_max_f32_e32 v146, v146, v155
	v_sub_f32_e32 v155, v146, v3
	v_cmp_ge_f32_e32 vcc, s31, v155
	s_cmp_eq_u64 vcc, exec
	v_max_f32_e32 v155, v3, v3
	s_cselect_b64 vcc, -1, 0
	v_max_f32_e32 v146, v155, v146
	v_sub_f32_e32 v155, v3, v146
	v_cndmask_b32_e32 v3, v146, v3, vcc
	v_sub_f32_e32 v4, v4, v3
	v_exp_f32_e32 v155, v155
	v_exp_f32_e32 v4, v4
	v_sub_f32_e32 v5, v5, v3
	v_exp_f32_e32 v5, v5
	v_sub_f32_e32 v6, v6, v3
	v_exp_f32_e32 v6, v6
	v_sub_f32_e32 v7, v7, v3
	v_exp_f32_e32 v7, v7
	v_sub_f32_e32 v9, v9, v3
	v_cndmask_b32_e64 v146, v155, 1.0, vcc
	v_add_f32_e32 v155, 0, v4
	v_exp_f32_e32 v9, v9
	v_sub_f32_e32 v10, v10, v3
	v_add_f32_e32 v155, v5, v155
	v_exp_f32_e32 v10, v10
	v_sub_f32_e32 v11, v11, v3
	v_add_f32_e32 v155, v6, v155
	v_exp_f32_e32 v11, v11
	v_sub_f32_e32 v147, v147, v3
	v_add_f32_e32 v155, v7, v155
	v_exp_f32_e32 v156, v147
	v_add_f32_e32 v155, v9, v155
	v_add_f32_e32 v155, v10, v155
	v_add_f32_e32 v155, v11, v155
	v_sub_f32_e32 v148, v148, v3
	v_add_f32_e32 v147, v156, v155
	v_exp_f32_e32 v155, v148
	v_sub_f32_e32 v148, v149, v3
	v_exp_f32_e32 v149, v148
	v_sub_f32_e32 v148, v150, v3
	v_exp_f32_e32 v150, v148
	v_sub_f32_e32 v148, v151, v3
	v_exp_f32_e32 v151, v148
	v_sub_f32_e32 v148, v152, v3
	v_add_f32_e32 v147, v155, v147
	v_exp_f32_e32 v152, v148
	v_sub_f32_e32 v148, v153, v3
	v_add_f32_e32 v147, v149, v147
	v_exp_f32_e32 v153, v148
	v_sub_f32_e32 v148, v154, v3
	v_add_f32_e32 v147, v150, v147
	v_exp_f32_e32 v154, v148
	v_sub_f32_e32 v8, v8, v3
	v_add_f32_e32 v147, v151, v147
	v_exp_f32_e32 v157, v8
	v_add_f32_e32 v147, v152, v147
	v_add_f32_e32 v147, v153, v147
	v_add_f32_e32 v147, v154, v147
	v_add_f32_e32 v147, v157, v147
	ds_bpermute_b32 v148, v241, v147
	v_cvt_pk_bf16_f32 v4, v4, v5
	v_cvt_pk_bf16_f32 v5, v6, v7
	v_cvt_pk_bf16_f32 v6, v9, v10
	v_cvt_pk_bf16_f32 v7, v11, v156
	v_cvt_pk_bf16_f32 v8, v155, v149
	v_cvt_pk_bf16_f32 v9, v150, v151
	v_cvt_pk_bf16_f32 v10, v152, v153
	v_cvt_pk_bf16_f32 v11, v154, v157
	s_nop 0
	v_permlane32_swap_b32_e32 v4, v6
	v_permlane32_swap_b32_e32 v5, v7
	v_permlane32_swap_b32_e32 v8, v10
	v_permlane32_swap_b32_e32 v9, v11
	v_cmp_gt_f32_e32 vcc, 1.0, v146
	s_cbranch_vccz .LBB0_506
	s_and_saveexec_b64 s[0:1], s[6:7]
	ds_write_b32 v222, v146
	s_or_b64 exec, exec, s[0:1]
	s_waitcnt lgkmcnt(0)
	v_add_u32_e32 v149, s2, v198
	ds_read_b128 v[150:153], v149 offset:96
	ds_read_b128 v[154:157], v149 offset:64
	ds_read_b128 v[158:161], v149 offset:32
	ds_read_b128 v[244:247], v149
	s_waitcnt lgkmcnt(0)
	v_pk_mul_f32 v[142:143], v[142:143], v[150:151]
	v_pk_mul_f32 v[138:139], v[138:139], v[154:155]
	v_pk_mul_f32 v[134:135], v[134:135], v[158:159]
	v_pk_mul_f32 v[144:145], v[144:145], v[152:153]
	v_pk_mul_f32 v[140:141], v[140:141], v[156:157]
	v_pk_mul_f32 v[136:137], v[136:137], v[160:161]
	v_pk_mul_f32 v[132:133], v[132:133], v[246:247]
	v_pk_mul_f32 v[130:131], v[130:131], v[244:245]
	v_pk_mul_f32 v[126:127], v[126:127], v[150:151]
	v_pk_mul_f32 v[122:123], v[122:123], v[154:155]
	v_pk_mul_f32 v[118:119], v[118:119], v[158:159]
	v_pk_mul_f32 v[128:129], v[128:129], v[152:153]
	v_pk_mul_f32 v[124:125], v[124:125], v[156:157]
	v_pk_mul_f32 v[120:121], v[120:121], v[160:161]
	v_pk_mul_f32 v[116:117], v[116:117], v[246:247]
	v_pk_mul_f32 v[114:115], v[114:115], v[244:245]
	v_pk_mul_f32 v[110:111], v[110:111], v[150:151]
	v_pk_mul_f32 v[106:107], v[106:107], v[154:155]
	v_pk_mul_f32 v[102:103], v[102:103], v[158:159]
	v_pk_mul_f32 v[112:113], v[112:113], v[152:153]
	v_pk_mul_f32 v[108:109], v[108:109], v[156:157]
	v_pk_mul_f32 v[104:105], v[104:105], v[160:161]
	v_pk_mul_f32 v[100:101], v[100:101], v[246:247]
	v_pk_mul_f32 v[98:99], v[98:99], v[244:245]
	v_pk_mul_f32 v[94:95], v[94:95], v[150:151]
	v_pk_mul_f32 v[90:91], v[90:91], v[154:155]
	v_pk_mul_f32 v[86:87], v[86:87], v[158:159]
	v_pk_mul_f32 v[96:97], v[96:97], v[152:153]
	v_pk_mul_f32 v[92:93], v[92:93], v[156:157]
	v_pk_mul_f32 v[88:89], v[88:89], v[160:161]
	v_pk_mul_f32 v[84:85], v[84:85], v[246:247]
	v_pk_mul_f32 v[82:83], v[82:83], v[244:245]

.LBB0_510:
	s_lshl_b32 s0, s25, 16
	s_and_b32 s0, s0, 0x10000
	v_lshl_or_b32 v3, s25, 7, v198
	s_add_i32 s25, s0, 0
	s_add_i32 s25, s25, s14
	v_add_u32_e32 v9, s25, v215
	v_sub_u32_e32 v3, v225, v3
	v_subrev_u32_e32 v3, s13, v3
	v_lshl_add_u32 v3, v3, 2, 0
	v_add_u32_e32 v3, 0x1fe50, v3
	ds_read_b32 v130, v3 offset:432
	ds_read_b32 v131, v3 offset:416
	ds_read_b32 v132, v3 offset:400
	ds_read_b32 v133, v3 offset:384
	ds_read_b32 v134, v3 offset:304
	ds_read_b32 v135, v3 offset:288
	ds_read_b32 v136, v3 offset:272
	ds_read_b32 v137, v3 offset:256
	ds_read_b32 v138, v3 offset:176
	ds_read_b32 v139, v3 offset:160
	ds_read_b32 v140, v3 offset:144
	ds_read_b32 v141, v3 offset:128
	ds_read_b32 v142, v3 offset:48
	ds_read_b32 v143, v3 offset:32
	ds_read_b32 v144, v3 offset:16
	ds_read_b32 v145, v3
	v_add_u32_e32 v4, v9, v216
	ds_read_b128 v[98:101], v4
	v_add_u32_e32 v4, v9, v217
	ds_read_b128 v[102:105], v4
	v_add_u32_e32 v4, v9, v218
	ds_read_b128 v[106:109], v4
	v_add_u32_e32 v4, v9, v219
	ds_read_b128 v[110:113], v4
	v_add_u32_e32 v4, v9, v220
	ds_read_b128 v[114:117], v4
	v_add_u32_e32 v4, v9, v221
	ds_read_b128 v[118:121], v4
	v_add_u32_e32 v4, v9, v223
	ds_read_b128 v[122:125], v4
	v_add_u32_e32 v4, v9, v224
	ds_read_b128 v[126:129], v4
	s_waitcnt lgkmcnt(7)
	v_mfma_f32_32x32x16_bf16 v[82:97], v[98:101], v[162:165], 0
	s_waitcnt lgkmcnt(6)
	v_mfma_f32_32x32x16_bf16 v[82:97], v[102:105], v[166:169], v[82:97]
	s_waitcnt lgkmcnt(5)
	v_mfma_f32_32x32x16_bf16 v[82:97], v[106:109], v[170:173], v[82:97]
	s_waitcnt lgkmcnt(4)
	v_mfma_f32_32x32x16_bf16 v[82:97], v[110:113], v[174:177], v[82:97]
	s_waitcnt lgkmcnt(3)
	v_mfma_f32_32x32x16_bf16 v[82:97], v[114:117], v[178:181], v[82:97]
	s_waitcnt lgkmcnt(2)
	v_mfma_f32_32x32x16_bf16 v[82:97], v[118:121], v[182:185], v[82:97]
	s_waitcnt lgkmcnt(1)
	v_mfma_f32_32x32x16_bf16 v[82:97], v[122:125], v[186:189], v[82:97]
	s_waitcnt lgkmcnt(0)
	v_mfma_f32_32x32x16_bf16 v[82:97], v[126:129], v[190:193], v[82:97]
	s_nop 7
	s_nop 4
	v_add_f32_e32 v4, v82, v130
	v_add_f32_e32 v5, v83, v131
	v_add_f32_e32 v6, v84, v132
	v_add_f32_e32 v7, v85, v133
	v_add_f32_e32 v8, v86, v134
	v_add_f32_e32 v9, v87, v135
	v_add_f32_e32 v10, v88, v136
	v_add_f32_e32 v11, v89, v137
	v_add_f32_e32 v13, v90, v138
	v_add_f32_e32 v14, v91, v139
	v_add_f32_e32 v15, v92, v140
	v_add_f32_e32 v16, v93, v141
	v_add_f32_e32 v17, v94, v142
	v_add_f32_e32 v82, v95, v143
	v_add_f32_e32 v83, v96, v144
	v_add_f32_e32 v84, v97, v145
	v_and_b32_e32 v85, 64, v206
	v_add_u32_e32 v85, 64, v85
	v_max_f32_e32 v3, v4, v5
	v_max3_f32 v3, v3, v6, v7
	v_max3_f32 v3, v3, v8, v9
	v_max3_f32 v3, v3, v10, v11
	v_max3_f32 v3, v3, v13, v14
	v_xor_b32_e32 v12, 32, v206
	v_max3_f32 v3, v3, v15, v16
	v_cmp_lt_i32_e32 vcc, v12, v85
	v_max3_f32 v3, v3, v17, v82
	v_max3_f32 v3, v3, v83, v84
	v_cndmask_b32_e32 v12, v206, v12, vcc
	v_lshlrev_b32_e32 v85, 2, v12
	ds_bpermute_b32 v12, v85, v3
	s_waitcnt lgkmcnt(0)
	v_max_f32_e32 v12, v12, v12
	v_max_f32_e32 v3, v3, v12
	v_sub_f32_e32 v12, v3, v237
	v_cmp_ge_f32_e32 vcc, s31, v12
	s_cmp_eq_u64 vcc, exec
	v_max_f32_e32 v12, v237, v237
	s_cselect_b64 vcc, -1, 0
	v_max_f32_e32 v3, v12, v3
	v_sub_f32_e32 v12, v237, v3
	v_cndmask_b32_e32 v3, v3, v237, vcc
	v_sub_f32_e32 v4, v4, v3
	v_exp_f32_e32 v4, v4
	v_sub_f32_e32 v5, v5, v3
	v_exp_f32_e32 v5, v5
	v_sub_f32_e32 v6, v6, v3
	v_exp_f32_e32 v6, v6
	v_sub_f32_e32 v7, v7, v3
	v_exp_f32_e32 v7, v7
	v_sub_f32_e32 v8, v8, v3
	v_add_f32_e32 v86, 0, v4
	v_exp_f32_e32 v8, v8
	v_sub_f32_e32 v9, v9, v3
	v_add_f32_e32 v86, v5, v86
	v_exp_f32_e32 v9, v9
	v_sub_f32_e32 v10, v10, v3
	v_add_f32_e32 v86, v6, v86
	v_exp_f32_e32 v10, v10
	v_sub_f32_e32 v11, v11, v3
	v_add_f32_e32 v86, v7, v86
	v_exp_f32_e32 v11, v11
	v_sub_f32_e32 v13, v13, v3
	v_add_f32_e32 v86, v8, v86
	v_exp_f32_e32 v87, v13
	v_add_f32_e32 v86, v9, v86
	v_add_f32_e32 v86, v10, v86
	v_add_f32_e32 v86, v11, v86
	v_sub_f32_e32 v14, v14, v3
	v_add_f32_e32 v13, v87, v86
	v_exp_f32_e32 v86, v14
	v_sub_f32_e32 v14, v15, v3
	v_exp_f32_e32 v15, v14
	v_sub_f32_e32 v14, v16, v3
	v_exp_f32_e32 v16, v14
	v_sub_f32_e32 v14, v17, v3
	v_exp_f32_e32 v17, v14
	v_sub_f32_e32 v14, v82, v3
	v_add_f32_e32 v13, v86, v13
	v_exp_f32_e32 v82, v14
	v_sub_f32_e32 v14, v83, v3
	v_add_f32_e32 v13, v15, v13
	v_exp_f32_e32 v83, v14
	v_sub_f32_e32 v14, v84, v3
	v_add_f32_e32 v13, v16, v13
	v_exp_f32_e32 v84, v14
	v_add_f32_e32 v13, v17, v13
	v_add_f32_e32 v13, v82, v13
	v_add_f32_e32 v13, v83, v13
	v_exp_f32_e32 v12, v12
	v_add_f32_e32 v13, v84, v13
	ds_bpermute_b32 v14, v85, v13
	v_cvt_pk_bf16_f32 v4, v4, v5
	v_cndmask_b32_e64 v12, v12, 1.0, vcc
	v_cvt_pk_bf16_f32 v5, v6, v7
	v_cvt_pk_bf16_f32 v6, v8, v9
	v_cvt_pk_bf16_f32 v7, v10, v11
	v_cvt_pk_bf16_f32 v8, v87, v86
	v_cvt_pk_bf16_f32 v9, v15, v16
	v_cvt_pk_bf16_f32 v10, v17, v82
	v_cvt_pk_bf16_f32 v11, v83, v84
	s_nop 0
	v_permlane32_swap_b32_e32 v4, v6
	v_permlane32_swap_b32_e32 v5, v7
	v_permlane32_swap_b32_e32 v8, v10
	v_permlane32_swap_b32_e32 v9, v11
	v_cmp_gt_f32_e32 vcc, 1.0, v12
	s_cbranch_vccz .LBB0_514
	s_and_saveexec_b64 s[0:1], s[6:7]
	ds_write_b32 v222, v12
	s_or_b64 exec, exec, s[0:1]
	s_waitcnt lgkmcnt(0)
	v_add_u32_e32 v15, s2, v198
	ds_read_b128 v[82:85], v15 offset:96
	ds_read_b128 v[86:89], v15 offset:64
	ds_read_b128 v[90:93], v15 offset:32
	ds_read_b128 v[94:97], v15
	s_waitcnt lgkmcnt(0)
	v_pk_mul_f32 v[30:31], v[30:31], v[82:83]
	v_pk_mul_f32 v[26:27], v[26:27], v[86:87]
	v_pk_mul_f32 v[22:23], v[22:23], v[90:91]
	v_pk_mul_f32 v[32:33], v[32:33], v[84:85]
	v_pk_mul_f32 v[28:29], v[28:29], v[88:89]
	v_pk_mul_f32 v[24:25], v[24:25], v[92:93]
	v_pk_mul_f32 v[20:21], v[20:21], v[96:97]
	v_pk_mul_f32 v[18:19], v[18:19], v[94:95]
	v_pk_mul_f32 v[46:47], v[46:47], v[82:83]
	v_pk_mul_f32 v[42:43], v[42:43], v[86:87]
	v_pk_mul_f32 v[38:39], v[38:39], v[90:91]
	v_pk_mul_f32 v[48:49], v[48:49], v[84:85]
	v_pk_mul_f32 v[44:45], v[44:45], v[88:89]
	v_pk_mul_f32 v[40:41], v[40:41], v[92:93]
	v_pk_mul_f32 v[36:37], v[36:37], v[96:97]
	v_pk_mul_f32 v[34:35], v[34:35], v[94:95]
	v_pk_mul_f32 v[62:63], v[62:63], v[82:83]
	v_pk_mul_f32 v[58:59], v[58:59], v[86:87]
	v_pk_mul_f32 v[54:55], v[54:55], v[90:91]
	v_pk_mul_f32 v[64:65], v[64:65], v[84:85]
	v_pk_mul_f32 v[60:61], v[60:61], v[88:89]
	v_pk_mul_f32 v[56:57], v[56:57], v[92:93]
	v_pk_mul_f32 v[52:53], v[52:53], v[96:97]
	v_pk_mul_f32 v[50:51], v[50:51], v[94:95]
	v_pk_mul_f32 v[78:79], v[78:79], v[82:83]
	v_pk_mul_f32 v[74:75], v[74:75], v[86:87]
	v_pk_mul_f32 v[70:71], v[70:71], v[90:91]
	v_pk_mul_f32 v[80:81], v[80:81], v[84:85]
	v_pk_mul_f32 v[76:77], v[76:77], v[88:89]
	v_pk_mul_f32 v[72:73], v[72:73], v[92:93]
	v_pk_mul_f32 v[68:69], v[68:69], v[96:97]
	v_pk_mul_f32 v[66:67], v[66:67], v[94:95]
